# P3 chain rewrite + hand-written fused diff-attention tile loop (2-deep K/V prefetch, V/P double-buffered in LDS) + L2 prefetch of residual tiles in P4/P6 epilogues
# baseline (speedup 1.0000x reference)
; __device__ __forceinline__ unsigned pk2(float lo, float hi) { f32x2 v = {lo, hi}; bf16x2_t b = __builtin_convertvector(v, bf16x2_t); return __builtin_bit_cast(unsigned, b); }
; __device__ __forceinline__ float bflo(unsigned u) { return __uint_as_float(u << 16); }
; __device__ __forceinline__ float bfhi(unsigned u) { return __uint_as_float(u & 0xffff0000u); }
;     __device__ __forceinline__ void fused(Acc& acc, const Unit& u, int wr, int wc, int fr, int fq, LAS unsigned char* lds, int wid, int lane) const {
;     ...
;         const int row0 = u.pm * BM + wr * 64 + fr; const int col0 = u.pn * BM + wc * 32 + 8 * fq;
; #pragma unroll
;         for (int ai = 0; ai < 2; ++ai)
; #pragma unroll
;             for (int mp = 0; mp < 2; ++mp) {
;                 u32x4 xr[2][2];
; #pragma unroll
;                 for (int mm = 0; mm < 2; ++mm)
; #pragma unroll
;                     for (int bj = 0; bj < 2; ++bj) { const size_t off = (size_t)(row0 + ai * HALF + (2 * mp + mm) * 16) * DM + col0 + bj * HALF; xr[mm][bj] = *(const u32x4*)(X + off); }
; #pragma unroll
;                 for (int mm = 0; mm < 2; ++mm) { const int m = 2 * mp + mm; float s = 0.f;
; #pragma unroll
;                     for (int bj = 0; bj < 2; ++bj) { const size_t off = (size_t)(row0 + ai * HALF + m * 16) * DM + col0 + bj * HALF;
;                         const u32x4 x = xr[mm][bj];
;                         const f32x4 v0 = acc[ai][bj][m][0] + (f32x4){bflo(x.x), bfhi(x.x), bflo(x.y), bfhi(x.y)}, v1 = acc[ai][bj][m][1] + (f32x4){bflo(x.z), bfhi(x.z), bflo(x.w), bfhi(x.w)};
;                         u32x4 w; w.x = pk2(v0[0], v0[1]); w.y = pk2(v0[2], v0[3]); w.z = pk2(v1[0], v1[1]); w.w = pk2(v1[2], v1[3]); *(u32x4*)(X1B + off) = w;
;                         s += (v0[0] * v0[0] + v0[1] * v0[1]) + (v0[2] * v0[2] + v0[3] * v0[3]) + (v1[0] * v1[0] + v1[1] * v1[1]) + (v1[2] * v1[2] + v1[3] * v1[3]); }
;                     s += __shfl_xor(s, 16); s += __shfl_xor(s, 32);
;                     if (fq == 0) P[(ai * HALF + wr * 64 + m * 16 + fr) * 4 + wc] = s; }
.LBB0_1032:
	s_add_u32 s4, s34, 0xf800000
	s_addc_u32 s5, s35, 0
	s_lshl_b32 s9, s10, 8
	s_add_i32 s1, s9, s44
	s_lshl_b32 s0, s39, 5
	v_or_b32_e32 v140, s1, v152
	s_lshl_b32 s1, s8, 8
	s_or_b32 s0, s1, s0
	v_and_or_b32 v138, v151, 24, s0
	v_ashrrev_i32_e32 v139, 31, v138
	v_lshlrev_b64 v[148:149], 1, v[138:139]
	v_lshl_add_u64 v[130:131], s[70:71], 0, v[148:149]
	s_mov_b64 s[0:1], 0x2000000
	v_ashrrev_i32_e32 v141, 31, v140
	v_lshl_add_u64 v[142:143], v[130:131], 0, s[0:1]
	v_lshlrev_b64 v[160:161], 12, v[140:141]
	v_lshl_add_u64 v[130:131], v[142:143], 0, v[160:161]
	s_barrier
	s_mov_b64 s[98:99], 0x20000
	s_mov_b64 s[100:101], 0x10000
	v_lshl_add_u64 v[156:157], v[130:131], 0, s[98:99]
	global_load_dword v158, v[156:157], off
	global_load_dword v158, v[156:157], off offset:256
	v_lshl_add_u64 v[156:157], v[156:157], 0, s[100:101]
	global_load_dword v158, v[156:157], off
	global_load_dword v158, v[156:157], off offset:256
	s_mov_b64 s[98:99], 0x50000
	v_lshl_add_u64 v[156:157], v[156:157], 0, s[98:99]
	global_load_dword v158, v[156:157], off
	global_load_dword v158, v[156:157], off offset:256
	v_lshl_add_u64 v[156:157], v[156:157], 0, s[100:101]
	global_load_dword v158, v[156:157], off
	global_load_dword v158, v[156:157], off offset:256
	v_lshl_add_u64 v[156:157], v[156:157], 0, s[100:101]
	global_load_dword v158, v[156:157], off
	global_load_dword v158, v[156:157], off offset:256
	v_lshl_add_u64 v[156:157], v[156:157], 0, s[100:101]
	global_load_dword v158, v[156:157], off
	global_load_dword v158, v[156:157], off offset:256
	global_load_dwordx4 v[152:155], v[130:131], off
	global_load_dwordx4 v[156:159], v[130:131], off offset:256
	v_or_b32_e32 v130, 16, v140
	v_ashrrev_i32_e32 v131, 31, v130
	v_lshlrev_b64 v[144:145], 12, v[130:131]
	v_lshl_add_u64 v[130:131], v[142:143], 0, v[144:145]
	global_load_dwordx4 v[134:137], v[130:131], off
	s_nop 0
	global_load_dwordx4 v[130:133], v[130:131], off offset:256
	v_mbcnt_lo_u32_b32 v146, -1, 0
	v_mbcnt_hi_u32_b32 v146, -1, v146
	v_and_b32_e32 v151, 64, v146
	s_lshl_b32 s0, s39, 2
	v_xor_b32_e32 v147, 16, v146
	v_add_u32_e32 v151, 64, v151
	v_xor_b32_e32 v162, 32, v146
	s_add_i32 s10, s0, 0
	v_cmp_lt_i32_e64 s[0:1], v147, v151
	v_lshl_add_u64 v[160:161], s[4:5], 0, v[160:161]
	v_cmp_gt_u32_e32 vcc, 16, v1
	v_cndmask_b32_e64 v147, v146, v147, s[0:1]
	v_cmp_lt_i32_e64 s[0:1], v162, v151
	v_lshlrev_b32_e32 v147, 2, v147
	s_waitcnt vmcnt(0)
	v_and_b32_e32 v163, 0xffff0000, v152
	v_cndmask_b32_e64 v146, v146, v162, s[0:1]
	v_lshlrev_b32_e32 v162, 16, v152
	v_lshlrev_b32_e32 v152, 16, v153
	v_and_b32_e32 v153, 0xffff0000, v153
	v_lshlrev_b32_e32 v166, 16, v156
	v_and_b32_e32 v167, 0xffff0000, v156
	v_lshlrev_b32_e32 v156, 16, v157
	v_and_b32_e32 v157, 0xffff0000, v157
	v_lshlrev_b32_e32 v164, 16, v154
	v_and_b32_e32 v165, 0xffff0000, v154
	v_lshlrev_b32_e32 v154, 16, v155
	v_and_b32_e32 v155, 0xffff0000, v155
	v_lshlrev_b32_e32 v168, 16, v158
	v_and_b32_e32 v169, 0xffff0000, v158
	v_pk_add_f32 v[128:129], v[128:129], v[152:153]
	v_pk_add_f32 v[126:127], v[126:127], v[162:163]
	v_pk_add_f32 v[120:121], v[120:121], v[156:157]
	v_pk_add_f32 v[118:119], v[118:119], v[166:167]
	v_lshlrev_b32_e32 v158, 16, v159
	v_and_b32_e32 v159, 0xffff0000, v159
	v_pk_add_f32 v[124:125], v[124:125], v[154:155]
	v_pk_add_f32 v[122:123], v[122:123], v[164:165]
	v_pk_add_f32 v[154:155], v[114:115], v[168:169]
	v_cvt_pk_bf16_f32 v114, v126, v127
	v_cvt_pk_bf16_f32 v115, v128, v129
	v_mul_f32_e32 v127, v127, v127
	v_mul_f32_e32 v129, v129, v129
	v_mul_f32_e32 v151, v119, v119
	v_mul_f32_e32 v156, v121, v121
	v_pk_add_f32 v[152:153], v[116:117], v[158:159]
	v_cvt_pk_bf16_f32 v116, v122, v123
	v_cvt_pk_bf16_f32 v117, v124, v125
	v_mul_f32_e32 v123, v123, v123
	v_mul_f32_e32 v125, v125, v125
	v_mul_f32_e32 v157, v155, v155
	v_fmac_f32_e32 v127, v126, v126
	v_fmac_f32_e32 v129, v128, v128
	v_fmac_f32_e32 v151, v118, v118
	v_fmac_f32_e32 v156, v120, v120
	v_mul_f32_e32 v158, v153, v153
	v_fmac_f32_e32 v123, v122, v122
	v_fmac_f32_e32 v125, v124, v124
	v_fmac_f32_e32 v157, v154, v154
	v_add_f32_e32 v122, v127, v129
	v_add_f32_e32 v124, v151, v156
	v_fmac_f32_e32 v158, v152, v152
	v_add_f32_e32 v122, v123, v122
	v_add_f32_e32 v123, v157, v124
	v_add_f32_e32 v122, v125, v122
	v_add_f32_e32 v123, v158, v123
	v_add_f32_e32 v124, v122, v123
	ds_bpermute_b32 v125, v147, v124
	v_lshl_add_u64 v[122:123], v[160:161], 0, v[148:149]
	v_lshlrev_b32_e32 v146, 2, v146
	global_store_dwordx4 v[122:123], v[114:117], off
	v_cvt_pk_bf16_f32 v118, v118, v119
	v_cvt_pk_bf16_f32 v119, v120, v121
	s_waitcnt lgkmcnt(0)
	v_add_f32_e32 v115, v124, v125
	ds_bpermute_b32 v116, v146, v115
	v_cvt_pk_bf16_f32 v120, v154, v155
	v_cvt_pk_bf16_f32 v121, v152, v153
	v_lshl_add_u32 v114, v150, 4, s10
	global_store_dwordx4 v[122:123], v[118:121], off offset:256
	s_and_saveexec_b64 s[0:1], vcc
	s_cbranch_execz .LBB0_1034
	s_waitcnt lgkmcnt(0)
	v_add_f32_e32 v115, v115, v116
	ds_write_b32 v114, v115

; __device__ __forceinline__ float bflo(unsigned u) { return __uint_as_float(u << 16); }
; __device__ __forceinline__ float bfhi(unsigned u) { return __uint_as_float(u & 0xffff0000u); }
;     __device__ __forceinline__ void operator()(const Acc& acc, const Unit& u, int wr, int wc, int fr, int fq) const {
;         const int row0 = u.pm * BM + wr * 64 + fr; const int col0 = u.pn * BM + wc * 32 + 8 * fq;
; #pragma unroll
;         for (int ai = 0; ai < 2; ++ai) {
;             u32x4 xr[4][2];
; #pragma unroll
;             for (int m = 0; m < 4; ++m)
; #pragma unroll
;                 for (int bj = 0; bj < 2; ++bj) xr[m][bj] = *(const u32x4*)(X1B + (size_t)(row0 + ai * HALF + m * 16) * DM + col0 + bj * HALF);
; #pragma unroll
;             for (int m = 0; m < 4; ++m)
; #pragma unroll
;                 for (int bj = 0; bj < 2; ++bj) { float* p = OUT + (size_t)(row0 + ai * HALF + m * 16) * DM + col0 + bj * HALF; const u32x4 x = xr[m][bj];
;                     *(f32x4*)p = (f32x4){bflo(x.x), bfhi(x.x), bflo(x.y), bfhi(x.y)} + acc[ai][bj][m][0]; *(f32x4*)(p + 4) = (f32x4){bflo(x.z), bfhi(x.z), bflo(x.w), bfhi(x.w)} + acc[ai][bj][m][1]; }
.LBB0_1207:
	v_lshl_add_u32 v148, s41, 8, v152
	v_lshl_or_b32 v144, s42, 8, v154
	v_ashrrev_i32_e32 v145, 31, v144
	v_ashrrev_i32_e32 v149, 31, v148
	v_lshl_add_u64 v[146:147], v[144:145], 1, s[8:9]
	v_lshlrev_b64 v[150:151], 12, v[148:149]
	v_or_b32_e32 v178, 16, v148
	v_lshl_add_u64 v[150:151], v[146:147], 0, v[150:151]
	v_ashrrev_i32_e32 v179, 31, v178
	s_mov_b64 s[98:99], 0x80000
	s_mov_b64 s[100:101], 0x10000
	v_lshl_add_u64 v[162:163], v[150:151], 0, s[98:99]
	global_load_dword v164, v[162:163], off
	global_load_dword v164, v[162:163], off offset:256
	v_lshl_add_u64 v[162:163], v[162:163], 0, s[100:101]
	global_load_dword v164, v[162:163], off
	global_load_dword v164, v[162:163], off offset:256
	v_lshl_add_u64 v[162:163], v[162:163], 0, s[100:101]
	global_load_dword v164, v[162:163], off
	global_load_dword v164, v[162:163], off offset:256
	v_lshl_add_u64 v[162:163], v[162:163], 0, s[100:101]
	global_load_dword v164, v[162:163], off
	global_load_dword v164, v[162:163], off offset:256
	global_load_dwordx4 v[158:161], v[150:151], off
	global_load_dwordx4 v[162:165], v[150:151], off offset:256
	v_lshlrev_b64 v[150:151], 12, v[178:179]
	v_lshl_add_u64 v[150:151], v[146:147], 0, v[150:151]
	global_load_dwordx4 v[166:169], v[150:151], off
	global_load_dwordx4 v[170:173], v[150:151], off offset:256
	v_or_b32_e32 v190, 32, v148
	v_ashrrev_i32_e32 v191, 31, v190
	v_lshlrev_b64 v[150:151], 12, v[190:191]
	v_lshl_add_u64 v[180:181], v[146:147], 0, v[150:151]
	global_load_dwordx4 v[174:177], v[180:181], off
	v_lshlrev_b64 v[186:187], 13, v[178:179]
	global_load_dwordx4 v[178:181], v[180:181], off offset:256
	v_or_b32_e32 v150, 48, v148
	v_ashrrev_i32_e32 v151, 31, v150
	v_lshlrev_b64 v[182:183], 13, v[148:149]
	v_lshlrev_b64 v[184:185], 12, v[150:151]
	v_lshlrev_b64 v[144:145], 2, v[144:145]
	v_lshl_add_u64 v[182:183], s[70:71], 0, v[182:183]
	v_lshl_add_u64 v[188:189], v[146:147], 0, v[184:185]
	v_lshl_add_u64 v[192:193], v[182:183], 0, v[144:145]
	v_lshl_add_u64 v[194:195], s[70:71], 0, v[186:187]
	global_load_dwordx4 v[182:185], v[188:189], off
	s_nop 0
	global_load_dwordx4 v[186:189], v[188:189], off offset:256
	v_lshl_add_u64 v[194:195], v[194:195], 0, v[144:145]
	s_and_b64 vcc, exec, s[0:1]
	s_mov_b64 s[0:1], -1
	s_waitcnt vmcnt(0)
	v_lshlrev_b32_e32 v196, 16, v158
	v_and_b32_e32 v197, 0xffff0000, v158
	v_lshlrev_b32_e32 v158, 16, v159
	v_and_b32_e32 v159, 0xffff0000, v159
	v_lshlrev_b32_e32 v198, 16, v160
	v_and_b32_e32 v199, 0xffff0000, v160
	v_lshlrev_b32_e32 v160, 16, v161
	v_and_b32_e32 v161, 0xffff0000, v161
	v_lshlrev_b32_e32 v200, 16, v162
	v_and_b32_e32 v201, 0xffff0000, v162
	v_lshlrev_b32_e32 v162, 16, v163
	v_and_b32_e32 v163, 0xffff0000, v163
	v_lshlrev_b32_e32 v202, 16, v164
	v_and_b32_e32 v203, 0xffff0000, v164
	v_lshlrev_b32_e32 v164, 16, v165
	v_and_b32_e32 v165, 0xffff0000, v165
	v_pk_add_f32 v[126:127], v[126:127], v[158:159]
	v_pk_add_f32 v[122:123], v[122:123], v[160:161]
	v_pk_add_f32 v[118:119], v[118:119], v[162:163]
	v_pk_add_f32 v[114:115], v[114:115], v[164:165]
	v_lshlrev_b32_e32 v158, 16, v166
	v_and_b32_e32 v159, 0xffff0000, v166
	v_lshlrev_b32_e32 v160, 16, v167
	v_and_b32_e32 v161, 0xffff0000, v167
	v_lshlrev_b32_e32 v162, 16, v168
	v_and_b32_e32 v163, 0xffff0000, v168
	v_lshlrev_b32_e32 v164, 16, v169
	v_and_b32_e32 v165, 0xffff0000, v169
	v_lshlrev_b32_e32 v166, 16, v170
	v_and_b32_e32 v167, 0xffff0000, v170
	v_lshlrev_b32_e32 v168, 16, v171
	v_and_b32_e32 v169, 0xffff0000, v171
	v_lshlrev_b32_e32 v170, 16, v172
	v_and_b32_e32 v171, 0xffff0000, v172
	v_lshlrev_b32_e32 v172, 16, v173
	v_and_b32_e32 v173, 0xffff0000, v173
	v_pk_add_f32 v[124:125], v[124:125], v[196:197]
	v_pk_add_f32 v[110:111], v[110:111], v[160:161]
	v_pk_add_f32 v[108:109], v[108:109], v[158:159]
	v_pk_add_f32 v[94:95], v[94:95], v[172:173]
	v_pk_add_f32 v[92:93], v[92:93], v[170:171]
	v_pk_add_f32 v[120:121], v[120:121], v[198:199]
	v_pk_add_f32 v[116:117], v[116:117], v[200:201]
	v_pk_add_f32 v[112:113], v[112:113], v[202:203]
	global_store_dwordx4 v[192:193], v[124:127], off
	global_store_dwordx4 v[192:193], v[120:123], off offset:16
	global_store_dwordx4 v[192:193], v[116:119], off offset:512
	global_store_dwordx4 v[192:193], v[112:115], off offset:528
	v_pk_add_f32 v[106:107], v[106:107], v[164:165]
	v_pk_add_f32 v[104:105], v[104:105], v[162:163]
	v_pk_add_f32 v[102:103], v[102:103], v[168:169]
	v_pk_add_f32 v[100:101], v[100:101], v[166:167]
	global_store_dwordx4 v[194:195], v[108:111], off
	global_store_dwordx4 v[194:195], v[104:107], off offset:16
	global_store_dwordx4 v[194:195], v[100:103], off offset:512
	global_store_dwordx4 v[194:195], v[92:95], off offset:528
	s_nop 0
	v_add_u32_e32 v102, 0xb0, v148
	v_lshlrev_b64 v[92:93], 13, v[190:191]
	v_lshl_add_u64 v[92:93], s[70:71], 0, v[92:93]
	v_lshl_add_u64 v[100:101], v[92:93], 0, v[144:145]
	v_lshlrev_b32_e32 v92, 16, v174
	v_and_b32_e32 v93, 0xffff0000, v174
	v_lshlrev_b32_e32 v94, 16, v175
	v_and_b32_e32 v95, 0xffff0000, v175
	v_pk_add_f32 v[94:95], v[98:99], v[94:95]
	v_pk_add_f32 v[92:93], v[96:97], v[92:93]
	global_store_dwordx4 v[100:101], v[92:95], off
	v_add_u32_e32 v96, 0x80, v148
	v_ashrrev_i32_e32 v97, 31, v96
	v_lshlrev_b32_e32 v92, 16, v176
	v_and_b32_e32 v93, 0xffff0000, v176
	v_lshlrev_b32_e32 v94, 16, v177
	v_and_b32_e32 v95, 0xffff0000, v177
	v_pk_add_f32 v[90:91], v[90:91], v[94:95]
	v_pk_add_f32 v[88:89], v[88:89], v[92:93]
	global_store_dwordx4 v[100:101], v[88:91], off offset:16
	v_add_u32_e32 v98, 0x90, v148
	v_ashrrev_i32_e32 v99, 31, v98
	v_lshlrev_b32_e32 v88, 16, v178
	v_and_b32_e32 v89, 0xffff0000, v178
	v_lshlrev_b32_e32 v90, 16, v179
; __device__ __forceinline__ float bflo(unsigned u) { return __uint_as_float(u << 16); }
; __device__ __forceinline__ float bfhi(unsigned u) { return __uint_as_float(u & 0xffff0000u); }
;     __device__ __forceinline__ void operator()(const Acc& acc, const Unit& u, int wr, int wc, int fr, int fq) const {
;     ...
;         for (int ai = 0; ai < 2; ++ai) {
;             u32x4 xr[4][2];
; #pragma unroll
;             for (int m = 0; m < 4; ++m)
; #pragma unroll
;                 for (int bj = 0; bj < 2; ++bj) xr[m][bj] = *(const u32x4*)(X1B + (size_t)(row0 + ai * HALF + m * 16) * DM + col0 + bj * HALF);
; #pragma unroll
;             for (int m = 0; m < 4; ++m)
; #pragma unroll
;                 for (int bj = 0; bj < 2; ++bj) { float* p = OUT + (size_t)(row0 + ai * HALF + m * 16) * DM + col0 + bj * HALF; const u32x4 x = xr[m][bj];
;                     *(f32x4*)p = (f32x4){bflo(x.x), bfhi(x.x), bflo(x.y), bfhi(x.y)} + acc[ai][bj][m][0]; *(f32x4*)(p + 4) = (f32x4){bflo(x.z), bfhi(x.z), bflo(x.w), bfhi(x.w)} + acc[ai][bj][m][1]; }
;             asm volatile("" ::: "memory");
;         }
	v_and_b32_e32 v91, 0xffff0000, v179
	v_pk_add_f32 v[86:87], v[86:87], v[90:91]
	v_pk_add_f32 v[84:85], v[84:85], v[88:89]
	global_store_dwordx4 v[100:101], v[84:87], off offset:512
	v_ashrrev_i32_e32 v103, 31, v102
	s_nop 0
	v_lshlrev_b32_e32 v84, 16, v180
	v_and_b32_e32 v85, 0xffff0000, v180
	v_lshlrev_b32_e32 v86, 16, v181
	v_and_b32_e32 v87, 0xffff0000, v181
	v_pk_add_f32 v[78:79], v[78:79], v[86:87]
	v_pk_add_f32 v[76:77], v[76:77], v[84:85]
	global_store_dwordx4 v[100:101], v[76:79], off offset:528
	v_add_u32_e32 v100, 0xa0, v148
	v_ashrrev_i32_e32 v101, 31, v100
	v_lshlrev_b64 v[76:77], 13, v[150:151]
	v_lshl_add_u64 v[76:77], s[70:71], 0, v[76:77]
	v_lshl_add_u64 v[84:85], v[76:77], 0, v[144:145]
	v_lshlrev_b32_e32 v76, 16, v182
	v_and_b32_e32 v77, 0xffff0000, v182
	v_lshlrev_b32_e32 v78, 16, v183
	v_and_b32_e32 v79, 0xffff0000, v183
	v_pk_add_f32 v[78:79], v[82:83], v[78:79]
	v_pk_add_f32 v[76:77], v[80:81], v[76:77]
	global_store_dwordx4 v[84:85], v[76:79], off
	s_nop 1
	v_lshlrev_b32_e32 v76, 16, v184
	v_and_b32_e32 v77, 0xffff0000, v184
	v_lshlrev_b32_e32 v78, 16, v185
	v_and_b32_e32 v79, 0xffff0000, v185
	v_pk_add_f32 v[74:75], v[74:75], v[78:79]
	v_pk_add_f32 v[72:73], v[72:73], v[76:77]
	global_store_dwordx4 v[84:85], v[72:75], off offset:16
	s_nop 1
	v_lshlrev_b32_e32 v72, 16, v186
	v_and_b32_e32 v73, 0xffff0000, v186
	v_lshlrev_b32_e32 v74, 16, v187
	v_and_b32_e32 v75, 0xffff0000, v187
	v_pk_add_f32 v[70:71], v[70:71], v[74:75]
	v_pk_add_f32 v[68:69], v[68:69], v[72:73]
	global_store_dwordx4 v[84:85], v[68:71], off offset:512
	s_nop 1
	v_lshlrev_b32_e32 v68, 16, v188
	v_and_b32_e32 v69, 0xffff0000, v188
	v_lshlrev_b32_e32 v70, 16, v189
	v_and_b32_e32 v71, 0xffff0000, v189
	v_pk_add_f32 v[66:67], v[66:67], v[70:71]
	v_pk_add_f32 v[64:65], v[64:65], v[68:69]
	global_store_dwordx4 v[84:85], v[64:67], off offset:528
	s_nop 1
	v_lshlrev_b64 v[64:65], 12, v[96:97]
	v_lshl_add_u64 v[64:65], v[146:147], 0, v[64:65]
	global_load_dwordx4 v[68:71], v[64:65], off
	global_load_dwordx4 v[72:75], v[64:65], off offset:256
	v_lshlrev_b64 v[64:65], 12, v[98:99]
	v_lshl_add_u64 v[64:65], v[146:147], 0, v[64:65]
	global_load_dwordx4 v[76:79], v[64:65], off
	global_load_dwordx4 v[80:83], v[64:65], off offset:256
	v_lshlrev_b64 v[64:65], 12, v[100:101]
	v_lshl_add_u64 v[64:65], v[146:147], 0, v[64:65]
	global_load_dwordx4 v[84:87], v[64:65], off
	global_load_dwordx4 v[88:91], v[64:65], off offset:256
	v_lshlrev_b64 v[64:65], 12, v[102:103]
	v_lshl_add_u64 v[64:65], v[146:147], 0, v[64:65]
	global_load_dwordx4 v[92:95], v[64:65], off
	s_nop 0
	global_load_dwordx4 v[64:67], v[64:65], off offset:256
	v_lshlrev_b64 v[96:97], 13, v[96:97]
	v_lshl_add_u64 v[96:97], s[70:71], 0, v[96:97]
	v_lshl_add_u64 v[96:97], v[96:97], 0, v[144:145]
	s_waitcnt vmcnt(7)
	v_lshlrev_b32_e32 v104, 16, v68
	v_and_b32_e32 v105, 0xffff0000, v68
	v_lshlrev_b32_e32 v68, 16, v69
	v_and_b32_e32 v69, 0xffff0000, v69
	v_pk_add_f32 v[62:63], v[62:63], v[68:69]
	v_pk_add_f32 v[60:61], v[60:61], v[104:105]
	global_store_dwordx4 v[96:97], v[60:63], off
	s_nop 1
	v_lshlrev_b32_e32 v60, 16, v70
	v_and_b32_e32 v61, 0xffff0000, v70
	v_lshlrev_b32_e32 v62, 16, v71
	v_and_b32_e32 v63, 0xffff0000, v71
	v_pk_add_f32 v[58:59], v[58:59], v[62:63]
	v_pk_add_f32 v[56:57], v[56:57], v[60:61]
	global_store_dwordx4 v[96:97], v[56:59], off offset:16
	s_waitcnt vmcnt(8)
	s_nop 0
	v_lshlrev_b32_e32 v56, 16, v72
	v_and_b32_e32 v57, 0xffff0000, v72
	v_lshlrev_b32_e32 v58, 16, v73
	v_and_b32_e32 v59, 0xffff0000, v73
	v_pk_add_f32 v[54:55], v[54:55], v[58:59]
	v_pk_add_f32 v[52:53], v[52:53], v[56:57]
	global_store_dwordx4 v[96:97], v[52:55], off offset:512
	s_nop 1
	v_lshlrev_b32_e32 v52, 16, v74
	v_and_b32_e32 v53, 0xffff0000, v74
	v_lshlrev_b32_e32 v54, 16, v75
	v_and_b32_e32 v55, 0xffff0000, v75
	v_pk_add_f32 v[46:47], v[46:47], v[54:55]
	v_pk_add_f32 v[44:45], v[44:45], v[52:53]
	global_store_dwordx4 v[96:97], v[44:47], off offset:528
	s_nop 1
	v_lshlrev_b64 v[44:45], 13, v[98:99]
	v_lshl_add_u64 v[44:45], s[70:71], 0, v[44:45]
	v_lshl_add_u64 v[52:53], v[44:45], 0, v[144:145]
	s_waitcnt vmcnt(9)
; __device__ __forceinline__ float bflo(unsigned u) { return __uint_as_float(u << 16); }
; __device__ __forceinline__ float bfhi(unsigned u) { return __uint_as_float(u & 0xffff0000u); }
;     __device__ __forceinline__ void operator()(const Acc& acc, const Unit& u, int wr, int wc, int fr, int fq) const {
;     ...
;             for (int m = 0; m < 4; ++m)
; #pragma unroll
;                 for (int bj = 0; bj < 2; ++bj) { float* p = OUT + (size_t)(row0 + ai * HALF + m * 16) * DM + col0 + bj * HALF; const u32x4 x = xr[m][bj];
;                     *(f32x4*)p = (f32x4){bflo(x.x), bfhi(x.x), bflo(x.y), bfhi(x.y)} + acc[ai][bj][m][0]; *(f32x4*)(p + 4) = (f32x4){bflo(x.z), bfhi(x.z), bflo(x.w), bfhi(x.w)} + acc[ai][bj][m][1]; }
;             asm volatile("" ::: "memory");
	v_lshlrev_b32_e32 v44, 16, v76
	v_and_b32_e32 v45, 0xffff0000, v76
	v_lshlrev_b32_e32 v46, 16, v77
	v_and_b32_e32 v47, 0xffff0000, v77
	v_pk_add_f32 v[46:47], v[50:51], v[46:47]
	v_pk_add_f32 v[44:45], v[48:49], v[44:45]
	global_store_dwordx4 v[52:53], v[44:47], off
	s_nop 1
	v_lshlrev_b32_e32 v44, 16, v78
	v_and_b32_e32 v45, 0xffff0000, v78
	v_lshlrev_b32_e32 v46, 16, v79
	v_and_b32_e32 v47, 0xffff0000, v79
	v_pk_add_f32 v[42:43], v[42:43], v[46:47]
	v_pk_add_f32 v[40:41], v[40:41], v[44:45]
	global_store_dwordx4 v[52:53], v[40:43], off offset:16
	s_waitcnt vmcnt(10)
	s_nop 0
	v_lshlrev_b32_e32 v40, 16, v80
	v_and_b32_e32 v41, 0xffff0000, v80
	v_lshlrev_b32_e32 v42, 16, v81
	v_and_b32_e32 v43, 0xffff0000, v81
	v_pk_add_f32 v[38:39], v[38:39], v[42:43]
	v_pk_add_f32 v[36:37], v[36:37], v[40:41]
	global_store_dwordx4 v[52:53], v[36:39], off offset:512
	s_nop 1
	v_lshlrev_b32_e32 v36, 16, v82
	v_and_b32_e32 v37, 0xffff0000, v82
	v_lshlrev_b32_e32 v38, 16, v83
	v_and_b32_e32 v39, 0xffff0000, v83
	v_pk_add_f32 v[30:31], v[30:31], v[38:39]
	v_pk_add_f32 v[28:29], v[28:29], v[36:37]
	global_store_dwordx4 v[52:53], v[28:31], off offset:528
	s_nop 1
	v_lshlrev_b64 v[28:29], 13, v[100:101]
	v_lshl_add_u64 v[28:29], s[70:71], 0, v[28:29]
	v_lshl_add_u64 v[36:37], v[28:29], 0, v[144:145]
	s_waitcnt vmcnt(11)
	v_lshlrev_b32_e32 v28, 16, v84
	v_and_b32_e32 v29, 0xffff0000, v84
	v_lshlrev_b32_e32 v30, 16, v85
	v_and_b32_e32 v31, 0xffff0000, v85
	v_pk_add_f32 v[30:31], v[34:35], v[30:31]
	v_pk_add_f32 v[28:29], v[32:33], v[28:29]
	global_store_dwordx4 v[36:37], v[28:31], off
	s_nop 1
	v_lshlrev_b32_e32 v28, 16, v86
	v_and_b32_e32 v29, 0xffff0000, v86
	v_lshlrev_b32_e32 v30, 16, v87
	v_and_b32_e32 v31, 0xffff0000, v87
	v_pk_add_f32 v[26:27], v[26:27], v[30:31]
	v_pk_add_f32 v[24:25], v[24:25], v[28:29]
	global_store_dwordx4 v[36:37], v[24:27], off offset:16
	s_waitcnt vmcnt(12)
	s_nop 0
	v_lshlrev_b32_e32 v24, 16, v88
	v_and_b32_e32 v25, 0xffff0000, v88
	v_lshlrev_b32_e32 v26, 16, v89
	v_and_b32_e32 v27, 0xffff0000, v89
	v_pk_add_f32 v[22:23], v[22:23], v[26:27]
	v_pk_add_f32 v[20:21], v[20:21], v[24:25]
	global_store_dwordx4 v[36:37], v[20:23], off offset:512
	s_nop 1
	v_lshlrev_b32_e32 v20, 16, v90
	v_and_b32_e32 v21, 0xffff0000, v90
	v_lshlrev_b32_e32 v22, 16, v91
	v_and_b32_e32 v23, 0xffff0000, v91
	v_pk_add_f32 v[14:15], v[14:15], v[22:23]
	v_pk_add_f32 v[12:13], v[12:13], v[20:21]
	global_store_dwordx4 v[36:37], v[12:15], off offset:528
	s_nop 1
	v_lshlrev_b64 v[12:13], 13, v[102:103]
	v_lshl_add_u64 v[12:13], s[70:71], 0, v[12:13]
	v_lshl_add_u64 v[20:21], v[12:13], 0, v[144:145]
	s_waitcnt vmcnt(13)
	v_lshlrev_b32_e32 v12, 16, v92
	v_and_b32_e32 v13, 0xffff0000, v92
	v_lshlrev_b32_e32 v14, 16, v93
	v_and_b32_e32 v15, 0xffff0000, v93
	v_pk_add_f32 v[14:15], v[18:19], v[14:15]
	v_pk_add_f32 v[12:13], v[16:17], v[12:13]
	global_store_dwordx4 v[20:21], v[12:15], off
	s_nop 1
	v_lshlrev_b32_e32 v12, 16, v94
	v_and_b32_e32 v13, 0xffff0000, v94
	v_lshlrev_b32_e32 v14, 16, v95
	v_and_b32_e32 v15, 0xffff0000, v95
	v_pk_add_f32 v[10:11], v[10:11], v[14:15]
	v_pk_add_f32 v[8:9], v[8:9], v[12:13]
	global_store_dwordx4 v[20:21], v[8:11], off offset:16
	s_waitcnt vmcnt(14)
	s_nop 0
	v_lshlrev_b32_e32 v8, 16, v64
	v_and_b32_e32 v9, 0xffff0000, v64
	v_lshlrev_b32_e32 v10, 16, v65
	v_and_b32_e32 v11, 0xffff0000, v65
	v_pk_add_f32 v[6:7], v[6:7], v[10:11]
	v_pk_add_f32 v[4:5], v[4:5], v[8:9]
	global_store_dwordx4 v[20:21], v[4:7], off offset:512
	s_nop 1
	v_lshlrev_b32_e32 v4, 16, v66
	v_and_b32_e32 v5, 0xffff0000, v66
	v_lshlrev_b32_e32 v6, 16, v67
	v_and_b32_e32 v7, 0xffff0000, v67
	v_pk_add_f32 v[2:3], v[2:3], v[6:7]
	v_pk_add_f32 v[0:1], v[0:1], v[4:5]
	global_store_dwordx4 v[20:21], v[0:3], off offset:528
	s_cbranch_vccnz .LBB0_1192
	s_andn2_b64 vcc, exec, s[6:7]
	s_cbranch_vccnz .LBB0_1191
	s_barrier
	s_branch .LBB0_1191

; __global__ void __launch_bounds__(NWAVES * 64, 2) mk_fwd(Args args) {
	.amdhsa_kernel _Z6mk_fwd4Args
		.amdhsa_group_segment_fixed_size 0
		.amdhsa_private_segment_fixed_size 0
		.amdhsa_kernarg_size 488
		.amdhsa_user_sgpr_count 2
		.amdhsa_user_sgpr_dispatch_ptr 0
		.amdhsa_user_sgpr_queue_ptr 0
		.amdhsa_user_sgpr_kernarg_segment_ptr 1
		.amdhsa_user_sgpr_dispatch_id 0
		.amdhsa_user_sgpr_kernarg_preload_length 0
		.amdhsa_user_sgpr_kernarg_preload_offset 0
		.amdhsa_user_sgpr_private_segment_size 0
		.amdhsa_uses_dynamic_stack 0
		.amdhsa_enable_private_segment 0
		.amdhsa_system_sgpr_workgroup_id_x 1
		.amdhsa_system_sgpr_workgroup_id_y 0
		.amdhsa_system_sgpr_workgroup_id_z 0
		.amdhsa_system_sgpr_workgroup_info 0
		.amdhsa_system_vgpr_workitem_id 0
		.amdhsa_next_free_vgpr 253
		.amdhsa_next_free_sgpr 102
		.amdhsa_accum_offset 256
		.amdhsa_reserve_vcc 1
		.amdhsa_float_round_mode_32 0
		.amdhsa_float_round_mode_16_64 0
		.amdhsa_float_denorm_mode_32 3
		.amdhsa_float_denorm_mode_16_64 3
		.amdhsa_dx10_clamp 1
		.amdhsa_ieee_mode 1
		.amdhsa_fp16_overflow 0
		.amdhsa_tg_split 0
		.amdhsa_exception_fp_ieee_invalid_op 0
		.amdhsa_exception_fp_denorm_src 0
		.amdhsa_exception_fp_ieee_div_zero 0
		.amdhsa_exception_fp_ieee_overflow 0
		.amdhsa_exception_fp_ieee_underflow 0
		.amdhsa_exception_fp_ieee_inexact 0
		.amdhsa_exception_int_div_zero 0
	.end_amdhsa_kernel

; __global__ void __launch_bounds__(NWAVES * 64, 2) mk_fwd(Args args) {
amdhsa.kernels:
  - .agpr_count:     0
    .args:
      - .offset:         0
        .size:           232
        .value_kind:     by_value
      - .offset:         232
        .size:           4
        .value_kind:     hidden_block_count_x
      - .offset:         236
        .size:           4
        .value_kind:     hidden_block_count_y
      - .offset:         240
        .size:           4
        .value_kind:     hidden_block_count_z
      - .offset:         244
        .size:           2
        .value_kind:     hidden_group_size_x
      - .offset:         246
        .size:           2
        .value_kind:     hidden_group_size_y
      - .offset:         248
        .size:           2
        .value_kind:     hidden_group_size_z
      - .offset:         250
        .size:           2
        .value_kind:     hidden_remainder_x
      - .offset:         252
        .size:           2
        .value_kind:     hidden_remainder_y
      - .offset:         254
        .size:           2
        .value_kind:     hidden_remainder_z
      - .offset:         272
        .size:           8
        .value_kind:     hidden_global_offset_x
      - .offset:         280
        .size:           8
        .value_kind:     hidden_global_offset_y
      - .offset:         288
        .size:           8
        .value_kind:     hidden_global_offset_z
      - .offset:         296
        .size:           2
        .value_kind:     hidden_grid_dims
      - .offset:         352
        .size:           4
        .value_kind:     hidden_dynamic_lds_size
    .group_segment_fixed_size: 0
    .kernarg_segment_align: 8
    .kernarg_segment_size: 488
    .language:       OpenCL C
    .language_version:
      - 2
      - 0
    .max_flat_workgroup_size: 512
    .name:           _Z6mk_fwd4Args
    .private_segment_fixed_size: 0
    .sgpr_count:     108
    .sgpr_spill_count: 24
    .symbol:         _Z6mk_fwd4Args.kd
    .uniform_work_group_size: 1
    .uses_dynamic_stack: false
    .vgpr_count:     253
    .vgpr_spill_count: 0
    .wavefront_size: 64
